# sample-row output projections (mini_gemm, phases 5 and 9): all K-split operand loads issued up front with counted waits instead of ~10 serialized vmcnt(0) round trips
# speedup vs baseline: 1.0043x; 1.0043x over previous
.LBB0_981:
	s_and_b32 s3, s4, 0x60
	v_or_b32_e32 v0, s3, v24
	s_and_b32 s2, s7, 0xffffffe0
	v_mul_u32_u24_e32 v0, 0xe00, v0
	v_or_b32_e32 v1, s2, v24
	v_lshlrev_b32_e32 v16, 1, v0
	s_waitcnt vmcnt(0)
	v_mad_i64_i32 v[146:147], s[14:15], v1, s6, v[20:21]
	v_lshl_add_u64 v[148:149], v[18:19], 0, v[16:17]
	v_or_b32_e32 v16, s3, v25
	s_ashr_i32 s3, s2, 31
	s_add_i32 s8, s8, s46
	s_add_i32 s7, s7, s50
	s_add_i32 s4, s4, s5
	s_cmpk_lt_i32 s8, 0x100
	global_load_dwordx4 v[0:3], v[146:147], off
	global_load_dwordx4 v[4:7], v[148:149], off
	global_load_dwordx4 v[30:33], v[146:147], off offset:32
	global_load_dwordx4 v[34:37], v[148:149], off offset:32
	global_load_dwordx4 v[38:41], v[146:147], off offset:64
	global_load_dwordx4 v[42:45], v[148:149], off offset:64
	global_load_dwordx4 v[46:49], v[146:147], off offset:96
	global_load_dwordx4 v[50:53], v[148:149], off offset:96
	global_load_dwordx4 v[54:57], v[146:147], off offset:128
	global_load_dwordx4 v[58:61], v[148:149], off offset:128
	global_load_dwordx4 v[62:65], v[146:147], off offset:160
	global_load_dwordx4 v[66:69], v[148:149], off offset:160
	global_load_dwordx4 v[70:73], v[146:147], off offset:192
	global_load_dwordx4 v[74:77], v[148:149], off offset:192
	global_load_dwordx4 v[78:81], v[146:147], off offset:224
	global_load_dwordx4 v[82:85], v[148:149], off offset:224
	global_load_dwordx4 v[86:89], v[146:147], off offset:256
	global_load_dwordx4 v[90:93], v[148:149], off offset:256
	global_load_dwordx4 v[94:97], v[146:147], off offset:288
	global_load_dwordx4 v[98:101], v[148:149], off offset:288
	global_load_dwordx4 v[102:105], v[146:147], off offset:320
	global_load_dwordx4 v[106:109], v[148:149], off offset:320
	global_load_dwordx4 v[110:113], v[146:147], off offset:352
	global_load_dwordx4 v[114:117], v[148:149], off offset:352
	global_load_dwordx4 v[118:121], v[146:147], off offset:384
	global_load_dwordx4 v[122:125], v[148:149], off offset:384
	global_load_dwordx4 v[126:129], v[146:147], off offset:416
	global_load_dwordx4 v[130:133], v[148:149], off offset:416
	global_load_dwordx4 v[134:137], v[146:147], off offset:448
	global_load_dwordx4 v[138:141], v[148:149], off offset:448
	global_load_dwordx4 v[142:145], v[146:147], off offset:480
	global_load_dwordx4 v[150:153], v[148:149], off offset:480
	global_load_dwordx4 v[154:157], v[146:147], off offset:512
	global_load_dwordx4 v[158:161], v[148:149], off offset:512
	global_load_dwordx4 v[162:165], v[146:147], off offset:544
	global_load_dwordx4 v[166:169], v[148:149], off offset:544
	global_load_dwordx4 v[170:173], v[146:147], off offset:576
	global_load_dwordx4 v[174:177], v[148:149], off offset:576
	global_load_dwordx4 v[178:181], v[146:147], off offset:608
	global_load_dwordx4 v[182:185], v[148:149], off offset:608
	global_load_dwordx4 v[186:189], v[146:147], off offset:640
	global_load_dwordx4 v[190:193], v[148:149], off offset:640
	global_load_dwordx4 v[194:197], v[146:147], off offset:672
	global_load_dwordx4 v[198:201], v[148:149], off offset:672
	global_load_dwordx4 v[202:205], v[146:147], off offset:704
	global_load_dwordx4 v[210:213], v[148:149], off offset:704
	global_load_dwordx4 v[214:217], v[146:147], off offset:736
	global_load_dwordx4 v[218:221], v[148:149], off offset:736
	global_load_dwordx4 v[222:225], v[146:147], off offset:768
	global_load_dwordx4 v[226:229], v[148:149], off offset:768
	global_load_dwordx4 v[230:233], v[146:147], off offset:800
	global_load_dwordx4 v[234:237], v[148:149], off offset:800
	global_load_dwordx4 v[238:241], v[146:147], off offset:832
	global_load_dwordx4 v[242:245], v[148:149], off offset:832
	global_load_dwordx4 v[246:249], v[146:147], off offset:864
	s_waitcnt vmcnt(53)
	v_mfma_f32_32x32x16_bf16 v[0:15], v[4:7], v[0:3], 0
	s_waitcnt vmcnt(51)
	v_mfma_f32_32x32x16_bf16 v[0:15], v[34:37], v[30:33], v[0:15]
	global_load_dwordx4 v[30:33], v[148:149], off offset:864
	s_waitcnt vmcnt(50)
	v_mfma_f32_32x32x16_bf16 v[0:15], v[42:45], v[38:41], v[0:15]
	s_waitcnt vmcnt(48)
	v_mfma_f32_32x32x16_bf16 v[0:15], v[50:53], v[46:49], v[0:15]
	s_waitcnt vmcnt(46)
	v_mfma_f32_32x32x16_bf16 v[0:15], v[58:61], v[54:57], v[0:15]
	s_waitcnt vmcnt(44)
	v_mfma_f32_32x32x16_bf16 v[0:15], v[66:69], v[62:65], v[0:15]
	s_waitcnt vmcnt(42)
	v_mfma_f32_32x32x16_bf16 v[0:15], v[74:77], v[70:73], v[0:15]
	s_waitcnt vmcnt(40)
	v_mfma_f32_32x32x16_bf16 v[0:15], v[82:85], v[78:81], v[0:15]
	s_waitcnt vmcnt(38)
	v_mfma_f32_32x32x16_bf16 v[0:15], v[90:93], v[86:89], v[0:15]
	s_waitcnt vmcnt(36)
	v_mfma_f32_32x32x16_bf16 v[0:15], v[98:101], v[94:97], v[0:15]
	s_waitcnt vmcnt(34)
	v_mfma_f32_32x32x16_bf16 v[0:15], v[106:109], v[102:105], v[0:15]
	s_waitcnt vmcnt(32)
	v_mfma_f32_32x32x16_bf16 v[0:15], v[114:117], v[110:113], v[0:15]
	s_waitcnt vmcnt(30)
	v_mfma_f32_32x32x16_bf16 v[0:15], v[122:125], v[118:121], v[0:15]
	s_waitcnt vmcnt(28)
	v_mfma_f32_32x32x16_bf16 v[0:15], v[130:133], v[126:129], v[0:15]
	s_waitcnt vmcnt(26)
	v_mfma_f32_32x32x16_bf16 v[0:15], v[138:141], v[134:137], v[0:15]
	s_waitcnt vmcnt(24)
	v_mfma_f32_32x32x16_bf16 v[0:15], v[150:153], v[142:145], v[0:15]
	s_waitcnt vmcnt(22)
	v_mfma_f32_32x32x16_bf16 v[0:15], v[158:161], v[154:157], v[0:15]
	s_waitcnt vmcnt(20)
	v_mfma_f32_32x32x16_bf16 v[0:15], v[166:169], v[162:165], v[0:15]
	s_waitcnt vmcnt(18)
	v_mfma_f32_32x32x16_bf16 v[0:15], v[174:177], v[170:173], v[0:15]
	s_waitcnt vmcnt(16)
	v_mfma_f32_32x32x16_bf16 v[0:15], v[182:185], v[178:181], v[0:15]
	s_waitcnt vmcnt(14)
	v_mfma_f32_32x32x16_bf16 v[0:15], v[190:193], v[186:189], v[0:15]
	s_waitcnt vmcnt(12)
	v_mfma_f32_32x32x16_bf16 v[0:15], v[198:201], v[194:197], v[0:15]
	s_waitcnt vmcnt(10)
	v_mfma_f32_32x32x16_bf16 v[0:15], v[210:213], v[202:205], v[0:15]
	s_waitcnt vmcnt(8)
	v_mfma_f32_32x32x16_bf16 v[0:15], v[218:221], v[214:217], v[0:15]
	s_waitcnt vmcnt(6)
	v_mfma_f32_32x32x16_bf16 v[0:15], v[226:229], v[222:225], v[0:15]
	s_waitcnt vmcnt(4)
	v_mfma_f32_32x32x16_bf16 v[0:15], v[234:237], v[230:233], v[0:15]
	s_waitcnt vmcnt(2)
	v_mfma_f32_32x32x16_bf16 v[0:15], v[242:245], v[238:241], v[0:15]
	s_waitcnt vmcnt(0)
	v_mfma_f32_32x32x16_bf16 v[0:15], v[30:33], v[246:249], v[0:15]
	v_add_u32_e32 v46, v28, v16
	v_ashrrev_i32_e32 v47, 31, v46
	v_add_u32_e32 v32, v27, v16
	v_ashrrev_i32_e32 v33, 31, v32
	v_lshl_add_u64 v[30:31], s[2:3], 1, v[22:23]
	v_lshlrev_b64 v[32:33], 12, v[32:33]
	v_lshl_add_u64 v[32:33], v[30:31], 0, v[32:33]
	v_lshlrev_b64 v[34:35], 12, v[46:47]
	v_lshl_add_u64 v[30:31], v[30:31], 0, v[34:35]
	s_nop 11
	ds_write2st64_b32 v29, v0, v1 offset1:1
	ds_write2st64_b32 v29, v2, v3 offset0:2 offset1:3
	ds_write2st64_b32 v29, v4, v5 offset0:4 offset1:5
	ds_write2st64_b32 v29, v6, v7 offset0:6 offset1:7
	ds_write2st64_b32 v29, v8, v9 offset0:8 offset1:9
	ds_write2st64_b32 v29, v10, v11 offset0:10 offset1:11
	ds_write2st64_b32 v29, v12, v13 offset0:12 offset1:13
	ds_write2st64_b32 v29, v14, v15 offset0:14 offset1:15
	s_waitcnt lgkmcnt(0)
	s_barrier
	ds_read2st64_b32 v[0:1], v26 offset1:8
	ds_read2st64_b32 v[2:3], v26 offset0:16 offset1:24
	ds_read2st64_b32 v[4:5], v26 offset0:32 offset1:40
	ds_read2st64_b32 v[6:7], v26 offset0:48 offset1:56
	ds_read2st64_b32 v[8:9], v26 offset0:64 offset1:72
	ds_read2st64_b32 v[10:11], v26 offset0:80 offset1:88
	ds_read2st64_b32 v[12:13], v26 offset0:96 offset1:104
	ds_read2st64_b32 v[14:15], v26 offset0:112 offset1:120
	s_waitcnt lgkmcnt(7)
	v_add_f32_e32 v0, 0, v0
	v_add_f32_e32 v1, 0, v1
	s_waitcnt lgkmcnt(6)
	v_add_f32_e32 v0, v0, v2
	v_add_f32_e32 v1, v1, v3
	s_waitcnt lgkmcnt(5)
	v_add_f32_e32 v0, v0, v4
	v_add_f32_e32 v1, v1, v5
	s_waitcnt lgkmcnt(4)
	v_add_f32_e32 v0, v0, v6
	v_add_f32_e32 v1, v1, v7
	s_waitcnt lgkmcnt(3)
	v_add_f32_e32 v0, v0, v8
	v_add_f32_e32 v1, v1, v9
	s_waitcnt lgkmcnt(2)
	v_add_f32_e32 v0, v0, v10
	v_add_f32_e32 v1, v1, v11
	s_waitcnt lgkmcnt(1)
	v_add_f32_e32 v0, v0, v12
	v_add_f32_e32 v1, v1, v13
	s_waitcnt lgkmcnt(0)
	v_add_f32_e32 v0, v0, v14
	v_add_f32_e32 v1, v1, v15
	v_cvt_pk_bf16_f32 v0, v0, s0
	v_cvt_pk_bf16_f32 v1, v1, s0
	global_store_short v[32:33], v0, off
	global_store_short v[30:31], v1, off
	s_barrier
	s_cbranch_scc1 .LBB0_981

.LBB0_1409:
	s_and_b32 s1, s2, 0x60
	v_or_b32_e32 v0, s1, v24
	s_and_b32 s0, s5, 0xffffffe0
	v_mul_u32_u24_e32 v0, 0xa00, v0
	v_or_b32_e32 v1, s0, v24
	v_lshlrev_b32_e32 v16, 1, v0
	v_mad_i64_i32 v[114:115], s[6:7], v1, s4, v[20:21]
	v_lshl_add_u64 v[116:117], v[18:19], 0, v[16:17]
	v_or_b32_e32 v16, s1, v25
	s_ashr_i32 s1, s0, 31
	s_add_i32 s47, s47, s46
	s_add_i32 s5, s5, s50
	s_add_i32 s2, s2, s3
	s_cmpk_lt_i32 s47, 0x100
	global_load_dwordx4 v[0:3], v[114:115], off
	global_load_dwordx4 v[4:7], v[116:117], off
	global_load_dwordx4 v[30:33], v[114:115], off offset:32
	global_load_dwordx4 v[34:37], v[116:117], off offset:32
	global_load_dwordx4 v[38:41], v[114:115], off offset:64
	global_load_dwordx4 v[42:45], v[116:117], off offset:64
	global_load_dwordx4 v[46:49], v[114:115], off offset:96
	global_load_dwordx4 v[50:53], v[116:117], off offset:96
	global_load_dwordx4 v[54:57], v[114:115], off offset:128
	global_load_dwordx4 v[58:61], v[116:117], off offset:128
	global_load_dwordx4 v[62:65], v[114:115], off offset:160
	global_load_dwordx4 v[66:69], v[116:117], off offset:160
	global_load_dwordx4 v[70:73], v[114:115], off offset:192
	global_load_dwordx4 v[74:77], v[116:117], off offset:192
	global_load_dwordx4 v[78:81], v[114:115], off offset:224
	global_load_dwordx4 v[82:85], v[116:117], off offset:224
	global_load_dwordx4 v[86:89], v[114:115], off offset:256
	global_load_dwordx4 v[90:93], v[116:117], off offset:256
	global_load_dwordx4 v[94:97], v[114:115], off offset:288
	global_load_dwordx4 v[98:101], v[116:117], off offset:288
	global_load_dwordx4 v[102:105], v[114:115], off offset:320
	global_load_dwordx4 v[106:109], v[116:117], off offset:320
	global_load_dwordx4 v[110:113], v[114:115], off offset:352
	global_load_dwordx4 v[118:121], v[116:117], off offset:352
	global_load_dwordx4 v[122:125], v[114:115], off offset:384
	global_load_dwordx4 v[126:129], v[116:117], off offset:384
	global_load_dwordx4 v[130:133], v[114:115], off offset:416
	global_load_dwordx4 v[134:137], v[116:117], off offset:416
	global_load_dwordx4 v[138:141], v[114:115], off offset:448
	global_load_dwordx4 v[142:145], v[116:117], off offset:448
	global_load_dwordx4 v[146:149], v[114:115], off offset:480
	global_load_dwordx4 v[150:153], v[116:117], off offset:480
	global_load_dwordx4 v[154:157], v[114:115], off offset:512
	global_load_dwordx4 v[158:161], v[116:117], off offset:512
	global_load_dwordx4 v[162:165], v[114:115], off offset:544
	global_load_dwordx4 v[166:169], v[116:117], off offset:544
	global_load_dwordx4 v[170:173], v[114:115], off offset:576
	global_load_dwordx4 v[174:177], v[116:117], off offset:576
	global_load_dwordx4 v[178:181], v[114:115], off offset:608
	global_load_dwordx4 v[182:185], v[116:117], off offset:608
	s_waitcnt vmcnt(38)
	v_mfma_f32_32x32x16_bf16 v[0:15], v[4:7], v[0:3], 0
	s_waitcnt vmcnt(36)
	v_mfma_f32_32x32x16_bf16 v[0:15], v[34:37], v[30:33], v[0:15]
	s_waitcnt vmcnt(34)
	v_mfma_f32_32x32x16_bf16 v[0:15], v[42:45], v[38:41], v[0:15]
	s_waitcnt vmcnt(32)
	v_mfma_f32_32x32x16_bf16 v[0:15], v[50:53], v[46:49], v[0:15]
	s_waitcnt vmcnt(30)
	v_mfma_f32_32x32x16_bf16 v[0:15], v[58:61], v[54:57], v[0:15]
	s_waitcnt vmcnt(28)
	v_mfma_f32_32x32x16_bf16 v[0:15], v[66:69], v[62:65], v[0:15]
	s_waitcnt vmcnt(26)
	v_mfma_f32_32x32x16_bf16 v[0:15], v[74:77], v[70:73], v[0:15]
	s_waitcnt vmcnt(24)
	v_mfma_f32_32x32x16_bf16 v[0:15], v[82:85], v[78:81], v[0:15]
	s_waitcnt vmcnt(22)
	v_mfma_f32_32x32x16_bf16 v[0:15], v[90:93], v[86:89], v[0:15]
	s_waitcnt vmcnt(20)
	v_mfma_f32_32x32x16_bf16 v[0:15], v[98:101], v[94:97], v[0:15]
	s_waitcnt vmcnt(18)
	v_mfma_f32_32x32x16_bf16 v[0:15], v[106:109], v[102:105], v[0:15]
	s_waitcnt vmcnt(16)
	v_mfma_f32_32x32x16_bf16 v[0:15], v[118:121], v[110:113], v[0:15]
	s_waitcnt vmcnt(14)
	v_mfma_f32_32x32x16_bf16 v[0:15], v[126:129], v[122:125], v[0:15]
	s_waitcnt vmcnt(12)
	v_mfma_f32_32x32x16_bf16 v[0:15], v[134:137], v[130:133], v[0:15]
	s_waitcnt vmcnt(10)
	v_mfma_f32_32x32x16_bf16 v[0:15], v[142:145], v[138:141], v[0:15]
	s_waitcnt vmcnt(8)
	v_mfma_f32_32x32x16_bf16 v[0:15], v[150:153], v[146:149], v[0:15]
	s_waitcnt vmcnt(6)
	v_mfma_f32_32x32x16_bf16 v[0:15], v[158:161], v[154:157], v[0:15]
	s_waitcnt vmcnt(4)
	v_mfma_f32_32x32x16_bf16 v[0:15], v[166:169], v[162:165], v[0:15]
	s_waitcnt vmcnt(2)
	v_mfma_f32_32x32x16_bf16 v[0:15], v[174:177], v[170:173], v[0:15]
	s_waitcnt vmcnt(0)
	v_mfma_f32_32x32x16_bf16 v[0:15], v[182:185], v[178:181], v[0:15]
	v_add_u32_e32 v46, v28, v16
	v_ashrrev_i32_e32 v47, 31, v46
	v_add_u32_e32 v36, v27, v16
	v_ashrrev_i32_e32 v37, 31, v36
	v_lshl_add_u64 v[34:35], s[0:1], 1, v[22:23]
	v_lshlrev_b64 v[36:37], 12, v[36:37]
	v_lshl_add_u64 v[36:37], v[34:35], 0, v[36:37]
	v_lshlrev_b64 v[38:39], 12, v[46:47]
	v_lshl_add_u64 v[34:35], v[34:35], 0, v[38:39]
	s_nop 11
	ds_write2st64_b32 v29, v0, v1 offset1:1
	ds_write2st64_b32 v29, v2, v3 offset0:2 offset1:3
	ds_write2st64_b32 v29, v4, v5 offset0:4 offset1:5
	ds_write2st64_b32 v29, v6, v7 offset0:6 offset1:7
	ds_write2st64_b32 v29, v8, v9 offset0:8 offset1:9
	ds_write2st64_b32 v29, v10, v11 offset0:10 offset1:11
	ds_write2st64_b32 v29, v12, v13 offset0:12 offset1:13
	ds_write2st64_b32 v29, v14, v15 offset0:14 offset1:15
	s_waitcnt lgkmcnt(0)
	s_barrier
	ds_read2st64_b32 v[0:1], v26 offset1:8
	ds_read2st64_b32 v[2:3], v26 offset0:16 offset1:24
	ds_read2st64_b32 v[4:5], v26 offset0:32 offset1:40
	ds_read2st64_b32 v[6:7], v26 offset0:48 offset1:56
	ds_read2st64_b32 v[8:9], v26 offset0:64 offset1:72
	ds_read2st64_b32 v[10:11], v26 offset0:80 offset1:88
	ds_read2st64_b32 v[12:13], v26 offset0:96 offset1:104
	ds_read2st64_b32 v[14:15], v26 offset0:112 offset1:120
	s_waitcnt lgkmcnt(7)
	v_add_f32_e32 v0, 0, v0
	v_add_f32_e32 v1, 0, v1
	s_waitcnt lgkmcnt(6)
	v_add_f32_e32 v0, v0, v2
	v_add_f32_e32 v1, v1, v3
	s_waitcnt lgkmcnt(5)
	v_add_f32_e32 v0, v0, v4
	v_add_f32_e32 v1, v1, v5
	s_waitcnt lgkmcnt(4)
	v_add_f32_e32 v0, v0, v6
	v_add_f32_e32 v1, v1, v7
	s_waitcnt lgkmcnt(3)
	v_add_f32_e32 v0, v0, v8
	v_add_f32_e32 v1, v1, v9
	s_waitcnt lgkmcnt(2)
	v_add_f32_e32 v0, v0, v10
	v_add_f32_e32 v1, v1, v11
	s_waitcnt lgkmcnt(1)
	v_add_f32_e32 v0, v0, v12
	v_add_f32_e32 v1, v1, v13
	s_waitcnt lgkmcnt(0)
	v_add_f32_e32 v0, v0, v14
	v_add_f32_e32 v1, v1, v15
	v_cvt_pk_bf16_f32 v0, v0, s0
	v_cvt_pk_bf16_f32 v1, v1, s0
	global_store_short v[36:37], v0, off
	global_store_short v[34:35], v1, off
	s_barrier
	s_cbranch_scc1 .LBB0_1409
